# FFN1 and OIN/EIN k-loops: next k-tile requested at the END of the step (after the MFMAs), one tile ahead of the one being waited for: 2 tiles outstanding at the wait, 1 during the math
# speedup vs baseline: 1.0051x; 1.0051x over previous
; template <int EPI>
; __device__ __forceinline__ void gemm_tile(const Params& p, int l, const u16* __restrict__ A, int lda, const u16* __restrict__ Bt, int K, int m0, int n0, unsigned char* smem) {
;     ...
;     for (int kt = 0; kt < nk; ++kt) {
;         if (((kt + 1) & 3) == wid && kt + 1 < nk) asm volatile("s_waitcnt vmcnt(0)" ::: "memory");
;         __builtin_amdgcn_s_barrier();
.Loin_w4:
	s_waitcnt vmcnt(4)
	s_branch .Loin_bar

; #define G_TILE(kt_, st_) do { const size_t ko_ = (size_t)(kt_) * 1024; unsigned char* d_ = smem + (st_) * 16384; \
;         _Pragma("unroll") for (int s_ = 0; s_ < 8; ++s_) GLDS16(Abase + (size_t)s_ * ksub + ko_ + voff, d_ + s_ * 1024); \
;         _Pragma("unroll") for (int s_ = 0; s_ < 8; ++s_) GLDS16(Bbase + (size_t)s_ * ksub + ko_ + voff, d_ + 8192 + s_ * 1024); } while (0)
; template <int EPI>
; __device__ __forceinline__ void gemm_tile(const Params& p, int l, const u16* __restrict__ A, int lda, const u16* __restrict__ Bt, int K, int m0, int n0, unsigned char* smem) {
;     ...
;     for (int kt = 0; kt < nk; ++kt) {
;         if (((kt + 1) & 3) == wid && kt + 1 < nk) asm volatile("s_waitcnt vmcnt(0)" ::: "memory");
;         __builtin_amdgcn_s_barrier();
;         asm volatile("" ::: "memory");
;         if ((kt & 3) == wid && kt + 4 < nk) G_TILE(kt + 4, stn);
;         const int so = st * 16384;
;         bf16x8 af[4], bv[4];
; #pragma unroll
;         for (int i = 0; i < 4; ++i) af[i] = *(const bf16x8*)(fa + so + i * 1024);
; #pragma unroll
;         for (int j = 0; j < 4; ++j) bv[j] = *(const bf16x8*)(fb + so + j * 1024);
;         __builtin_amdgcn_s_setprio(1);
; #pragma unroll
;         for (int i = 0; i < 4; ++i)
; #pragma unroll
;             for (int j = 0; j < 4; ++j) acc[i][j] = __builtin_amdgcn_mfma_f32_16x16x32_bf16(af[i], bv[j], acc[i][j], 0, 0, 0);
;         __builtin_amdgcn_s_setprio(0);
;         st = (st == 4) ? 0 : st + 1;
;         stn = (stn == 4) ? 0 : stn + 1;
.Loin_bar:
	s_barrier
	ds_read_b128 v[92:95], v104 offset:8192
	ds_read_b128 v[96:99], v104 offset:9216
	ds_read_b128 v[100:103], v104 offset:10240
	ds_read_b128 v[104:107], v104 offset:11264
	ds_read_b128 v[76:79], v88
	ds_read_b128 v[80:83], v88 offset:1024
	ds_read_b128 v[84:87], v88 offset:2048
	ds_read_b128 v[88:91], v88 offset:3072
	s_setprio 1
	s_waitcnt lgkmcnt(3)
	v_mfma_f32_16x16x32_bf16 v[62:65], v[76:79], v[92:95], v[62:65]
	v_mfma_f32_16x16x32_bf16 v[58:61], v[76:79], v[96:99], v[58:61]
	v_mfma_f32_16x16x32_bf16 v[54:57], v[76:79], v[100:103], v[54:57]
	v_mfma_f32_16x16x32_bf16 v[50:53], v[76:79], v[104:107], v[50:53]
	s_waitcnt lgkmcnt(2)
	v_mfma_f32_16x16x32_bf16 v[46:49], v[80:83], v[92:95], v[46:49]
	v_mfma_f32_16x16x32_bf16 v[42:45], v[80:83], v[96:99], v[42:45]
	v_mfma_f32_16x16x32_bf16 v[38:41], v[80:83], v[100:103], v[38:41]
	v_mfma_f32_16x16x32_bf16 v[34:37], v[80:83], v[104:107], v[34:37]
	s_waitcnt lgkmcnt(1)
	v_mfma_f32_16x16x32_bf16 v[30:33], v[84:87], v[92:95], v[30:33]
	v_mfma_f32_16x16x32_bf16 v[26:29], v[84:87], v[96:99], v[26:29]
	v_mfma_f32_16x16x32_bf16 v[22:25], v[84:87], v[100:103], v[22:25]
	v_mfma_f32_16x16x32_bf16 v[18:21], v[84:87], v[104:107], v[18:21]
	s_waitcnt lgkmcnt(0)
	v_mfma_f32_16x16x32_bf16 v[14:17], v[88:91], v[92:95], v[14:17]
	v_mfma_f32_16x16x32_bf16 v[10:13], v[88:91], v[96:99], v[10:13]
	v_mfma_f32_16x16x32_bf16 v[6:9], v[88:91], v[100:103], v[6:9]
	v_mfma_f32_16x16x32_bf16 v[2:5], v[88:91], v[104:107], v[2:5]
	s_setprio 0
	s_add_i32 s0, s0, 0x4000
	s_cmp_eq_u32 s0, 0x14000
	s_cselect_b32 s0, 0, s0
	v_add_u32_e32 v88, s0, v75
	v_add_u32_e32 v104, s0, v74
	s_add_i32 s36, s36, 1
	s_cmp_lt_u32 s36, 31
	s_cbranch_scc0 .Loin_nd
	s_add_i32 s1, s23, s37
	s_mov_b32 m0, s1
	s_add_i32 s1, s1, 0x400
	global_load_lds_dwordx4 v252, s[30:31]
	s_mov_b32 m0, s1
	s_add_i32 s1, s23, s38
	global_load_lds_dwordx4 v253, s[30:31]
	s_mov_b32 m0, s1
	s_add_i32 s1, s1, 0x400
	global_load_lds_dwordx4 v252, s[28:29]
	s_mov_b32 m0, s1
	s_add_u32 s30, s30, 0x400
	global_load_lds_dwordx4 v253, s[28:29]
	s_addc_u32 s31, s31, 0
	s_add_u32 s28, s28, 0x400
	s_addc_u32 s29, s29, 0
	s_add_i32 s23, s23, 0x4000
	s_cmp_eq_u32 s23, 0x14000
	s_cselect_b32 s23, 0, s23
.Loin_nd:
	s_cmp_lg_u32 s36, 31
	s_cbranch_scc1 .Loin_head
	s_branch .LBB0_277

; template <int EPI>
; __device__ __forceinline__ void gemm_tile3(const Params& p, int l, const u16* __restrict__ A, int lda, const u16* __restrict__ Bt, int K, int m0, int n0, unsigned char* smem) {
;     ...
;     for (int kt = 0; kt < nk; ++kt) {
;         if (((kt + 1) & 3) == wid && kt + 1 < nk) asm volatile("s_waitcnt vmcnt(0)" ::: "memory");
;         __builtin_amdgcn_s_barrier();
;         asm volatile("" ::: "memory");
;         if (((kt + 3) & 3) == wid && kt + 3 < nk) G3_TILE(kt + 3, stn);
;         const int so = st * 20480;
;         bf16x8 af[6], bv[4];
;         {
;             typedef __attribute__((address_space(3))) unsigned char lds_u8;
;             const unsigned la = (unsigned)(uintptr_t)(lds_u8*)(fa + so);
;             const unsigned lb = (unsigned)(uintptr_t)(lds_u8*)(fb + so);
;     ...
;             DSR128(bv[0], lb, 0); DSR128(bv[1], lb, 1024); DSR128(bv[2], lb, 2048); DSR128(bv[3], lb, 3072);
;             DSR128(af[0], la, 0); DSR128(af[1], la, 1024); DSR128(af[2], la, 2048); DSR128(af[3], la, 3072); DSR128(af[4], la, 4096); DSR128(af[5], la, 5120);
;         }
;         __builtin_amdgcn_sched_barrier(0);
;         asm volatile("s_waitcnt lgkmcnt(5)" : "+v"(bv[0]), "+v"(bv[1]), "+v"(bv[2]), "+v"(bv[3]), "+v"(af[0]));
;         __builtin_amdgcn_sched_barrier(0);
; #pragma unroll
;         for (int j = 0; j < 4; ++j) acc[0][j] = __builtin_amdgcn_mfma_f32_16x16x32_bf16(bv[j], af[0], acc[0][j], 0, 0, 0);
;         __builtin_amdgcn_sched_barrier(0);
;         asm volatile("s_waitcnt lgkmcnt(4)" : "+v"(af[1]));
;         __builtin_amdgcn_sched_barrier(0);
; #pragma unroll
;         for (int j = 0; j < 4; ++j) acc[1][j] = __builtin_amdgcn_mfma_f32_16x16x32_bf16(bv[j], af[1], acc[1][j], 0, 0, 0);
;         __builtin_amdgcn_sched_barrier(0);
;         asm volatile("s_waitcnt lgkmcnt(3)" : "+v"(af[2]));
;         __builtin_amdgcn_sched_barrier(0);
; #pragma unroll
;         for (int j = 0; j < 4; ++j) acc[2][j] = __builtin_amdgcn_mfma_f32_16x16x32_bf16(bv[j], af[2], acc[2][j], 0, 0, 0);
;         __builtin_amdgcn_sched_barrier(0);
;         asm volatile("s_waitcnt lgkmcnt(2)" : "+v"(af[3]));
;         __builtin_amdgcn_sched_barrier(0);
; #pragma unroll
;         for (int j = 0; j < 4; ++j) acc[3][j] = __builtin_amdgcn_mfma_f32_16x16x32_bf16(bv[j], af[3], acc[3][j], 0, 0, 0);
;         __builtin_amdgcn_sched_barrier(0);
.Lf1_bar:
	s_barrier
	ds_read_b128 v[110:113], v122 offset:0
	ds_read_b128 v[114:117], v122 offset:1024
	ds_read_b128 v[118:121], v122 offset:2048
	ds_read_b128 v[122:125], v122 offset:3072
	ds_read_b128 v[126:129], v0 offset:0
	ds_read_b128 v[130:133], v0 offset:1024
	ds_read_b128 v[134:137], v0 offset:2048
	ds_read_b128 v[138:141], v0 offset:3072
	ds_read_b128 v[142:145], v0 offset:4096
	ds_read_b128 v[146:149], v0 offset:5120
	s_setprio 1
	s_waitcnt lgkmcnt(5)
	s_nop 0
	v_mfma_f32_16x16x32_bf16 v[94:97], v[110:113], v[126:129], v[94:97]
	v_mfma_f32_16x16x32_bf16 v[90:93], v[114:117], v[126:129], v[90:93]
	v_mfma_f32_16x16x32_bf16 v[86:89], v[118:121], v[126:129], v[86:89]
	v_mfma_f32_16x16x32_bf16 v[82:85], v[122:125], v[126:129], v[82:85]
	s_waitcnt lgkmcnt(4)
	s_nop 0
	v_mfma_f32_16x16x32_bf16 v[78:81], v[110:113], v[130:133], v[78:81]
	v_mfma_f32_16x16x32_bf16 v[74:77], v[114:117], v[130:133], v[74:77]
	v_mfma_f32_16x16x32_bf16 v[66:69], v[118:121], v[130:133], v[66:69]
	v_mfma_f32_16x16x32_bf16 v[70:73], v[122:125], v[130:133], v[70:73]
	s_waitcnt lgkmcnt(3)
	s_nop 0
	v_mfma_f32_16x16x32_bf16 v[62:65], v[110:113], v[134:137], v[62:65]
	v_mfma_f32_16x16x32_bf16 v[58:61], v[114:117], v[134:137], v[58:61]
	v_mfma_f32_16x16x32_bf16 v[50:53], v[118:121], v[134:137], v[50:53]
	v_mfma_f32_16x16x32_bf16 v[54:57], v[122:125], v[134:137], v[54:57]
	s_waitcnt lgkmcnt(2)
	s_nop 0
	v_mfma_f32_16x16x32_bf16 v[46:49], v[110:113], v[138:141], v[46:49]
	v_mfma_f32_16x16x32_bf16 v[42:45], v[114:117], v[138:141], v[42:45]
	v_mfma_f32_16x16x32_bf16 v[34:37], v[118:121], v[138:141], v[34:37]
	v_mfma_f32_16x16x32_bf16 v[38:41], v[122:125], v[138:141], v[38:41]
	s_waitcnt lgkmcnt(1)
	s_nop 0
	v_mfma_f32_16x16x32_bf16 v[30:33], v[110:113], v[142:145], v[30:33]
	v_mfma_f32_16x16x32_bf16 v[26:29], v[114:117], v[142:145], v[26:29]
	v_mfma_f32_16x16x32_bf16 v[18:21], v[118:121], v[142:145], v[18:21]
	v_mfma_f32_16x16x32_bf16 v[22:25], v[122:125], v[142:145], v[22:25]
	s_waitcnt lgkmcnt(0)
	s_add_i32 s50, s50, 0x5000
	s_add_i32 s16, s16, 1
	v_mfma_f32_16x16x32_bf16 v[14:17], v[110:113], v[146:149], v[14:17]
	s_cmp_eq_u32 s50, 0x14000
	s_cselect_b32 s50, 0, s50
	v_mfma_f32_16x16x32_bf16 v[10:13], v[114:117], v[146:149], v[10:13]
	s_cmp_lg_u32 s16, 31
	v_mfma_f32_16x16x32_bf16 v[6:9], v[118:121], v[146:149], v[6:9]
	v_mfma_f32_16x16x32_bf16 v[2:5], v[122:125], v[146:149], v[2:5]
	v_add_u32_e32 v110, s50, v109
	v_add_u32_e32 v122, 0x3000, v110
	v_add_u32_e32 v0, s50, v108
	s_setprio 0
	s_cmp_lt_u32 s16, 31
	s_cbranch_scc0 .Lf1_nd
	s_add_i32 s17, s51, s54
	s_add_i32 s18, s51, s0
	s_mov_b32 m0, s17
	s_add_i32 s17, s17, 0x400
	global_load_lds_dwordx4 v252, s[28:29]
	s_mov_b32 m0, s17
	s_add_i32 s17, s17, 0x400
	global_load_lds_dwordx4 v253, s[28:29]
	s_mov_b32 m0, s17
	s_nop 0
	global_load_lds_dwordx4 v254, s[28:29]
	s_mov_b32 m0, s18
	s_add_i32 s18, s18, 0x400
	global_load_lds_dwordx4 v252, s[30:31]
	s_mov_b32 m0, s18
	s_add_u32 s28, s28, 0x400
	global_load_lds_dwordx4 v253, s[30:31]
	s_addc_u32 s29, s29, 0
	s_add_u32 s30, s30, 0x400
	s_addc_u32 s31, s31, 0
	s_add_i32 s51, s51, 0x5000
	s_cmp_eq_u32 s51, 0x14000
	s_cselect_b32 s51, 0, s51
.Lf1_nd:
	s_cmp_lg_u32 s16, 31
	s_cbranch_scc1 .Lf1_head
	s_branch .LBB0_892
